# v26 + K/V image builder V-transpose pass with all row loads in flight
# speedup vs baseline: 1.0195x; 1.0072x over previous
.LBB0_1516:
	v_or_b32_e32 v66, s0, v175
	v_lshlrev_b32_e32 v14, 1, v66
	v_add_u32_e32 v14, 0x600, v14
	global_load_ushort v16, v14, s[6:7]
	global_load_ushort v17, v14, s[6:7] offset:3072
	v_add_u32_e32 v15, 0x1800, v14
	global_load_ushort v18, v15, s[6:7]
	global_load_ushort v19, v15, s[6:7] offset:3072
	v_add_u32_e32 v15, 0x3000, v14
	global_load_ushort v20, v15, s[6:7]
	global_load_ushort v21, v15, s[6:7] offset:3072
	v_add_u32_e32 v15, 0x4800, v14
	global_load_ushort v22, v15, s[6:7]
	global_load_ushort v23, v15, s[6:7] offset:3072
	v_add_u32_e32 v15, 0x6000, v14
	global_load_ushort v24, v15, s[6:7]
	global_load_ushort v25, v15, s[6:7] offset:3072
	v_add_u32_e32 v15, 0x7800, v14
	global_load_ushort v26, v15, s[6:7]
	global_load_ushort v27, v15, s[6:7] offset:3072
	v_add_u32_e32 v15, 0x9000, v14
	global_load_ushort v28, v15, s[6:7]
	global_load_ushort v29, v15, s[6:7] offset:3072
	v_add_u32_e32 v15, 0xa800, v14
	global_load_ushort v30, v15, s[6:7]
	global_load_ushort v31, v15, s[6:7] offset:3072
	v_add_u32_e32 v15, 0xc000, v14
	global_load_ushort v32, v15, s[6:7]
	global_load_ushort v33, v15, s[6:7] offset:3072
	v_add_u32_e32 v15, 0xd800, v14
	global_load_ushort v34, v15, s[6:7]
	global_load_ushort v35, v15, s[6:7] offset:3072
	v_add_u32_e32 v15, 0xf000, v14
	global_load_ushort v36, v15, s[6:7]
	global_load_ushort v37, v15, s[6:7] offset:3072
	v_add_u32_e32 v15, 0x10800, v14
	global_load_ushort v38, v15, s[6:7]
	global_load_ushort v39, v15, s[6:7] offset:3072
	v_add_u32_e32 v15, 0x12000, v14
	global_load_ushort v40, v15, s[6:7]
	global_load_ushort v41, v15, s[6:7] offset:3072
	v_add_u32_e32 v15, 0x13800, v14
	global_load_ushort v42, v15, s[6:7]
	global_load_ushort v43, v15, s[6:7] offset:3072
	v_add_u32_e32 v15, 0x15000, v14
	global_load_ushort v44, v15, s[6:7]
	global_load_ushort v45, v15, s[6:7] offset:3072
	v_add_u32_e32 v15, 0x16800, v14
	global_load_ushort v46, v15, s[6:7]
	global_load_ushort v47, v15, s[6:7] offset:3072
	v_add_u32_e32 v15, 0x18000, v14
	global_load_ushort v48, v15, s[6:7]
	global_load_ushort v49, v15, s[6:7] offset:3072
	v_add_u32_e32 v15, 0x19800, v14
	global_load_ushort v50, v15, s[6:7]
	global_load_ushort v51, v15, s[6:7] offset:3072
	v_add_u32_e32 v15, 0x1b000, v14
	global_load_ushort v52, v15, s[6:7]
	global_load_ushort v53, v15, s[6:7] offset:3072
	v_add_u32_e32 v15, 0x1c800, v14
	global_load_ushort v54, v15, s[6:7]
	global_load_ushort v55, v15, s[6:7] offset:3072
	v_add_u32_e32 v15, 0x1e000, v14
	global_load_ushort v56, v15, s[6:7]
	global_load_ushort v57, v15, s[6:7] offset:3072
	v_add_u32_e32 v15, 0x1f800, v14
	global_load_ushort v58, v15, s[6:7]
	global_load_ushort v59, v15, s[6:7] offset:3072
	v_add_u32_e32 v15, 0x21000, v14
	global_load_ushort v60, v15, s[6:7]
	global_load_ushort v61, v15, s[6:7] offset:3072
	v_add_u32_e32 v15, 0x22800, v14
	global_load_ushort v62, v15, s[6:7]
	global_load_ushort v63, v15, s[6:7] offset:3072
	v_add_u32_e32 v15, 0x24000, v14
	global_load_ushort v178, v15, s[6:7]
	global_load_ushort v179, v15, s[6:7] offset:3072
	v_add_u32_e32 v15, 0x25800, v14
	global_load_ushort v180, v15, s[6:7]
	global_load_ushort v181, v15, s[6:7] offset:3072
	v_add_u32_e32 v15, 0x27000, v14
	global_load_ushort v182, v15, s[6:7]
	global_load_ushort v183, v15, s[6:7] offset:3072
	v_add_u32_e32 v15, 0x28800, v14
	global_load_ushort v184, v15, s[6:7]
	global_load_ushort v185, v15, s[6:7] offset:3072
	v_add_u32_e32 v15, 0x2a000, v14
	global_load_ushort v186, v15, s[6:7]
	global_load_ushort v187, v15, s[6:7] offset:3072
	v_add_u32_e32 v15, 0x2b800, v14
	global_load_ushort v188, v15, s[6:7]
	global_load_ushort v189, v15, s[6:7] offset:3072
	v_add_u32_e32 v15, 0x2d000, v14
	global_load_ushort v190, v15, s[6:7]
	global_load_ushort v191, v15, s[6:7] offset:3072
	v_add_u32_e32 v15, 0x2e800, v14
	global_load_ushort v192, v15, s[6:7]
	global_load_ushort v193, v15, s[6:7] offset:3072
	v_lshlrev_b32_e32 v66, 4, v66
	s_waitcnt vmcnt(56)
	v_lshl_or_b32 v0, v17, 16, v16
	v_lshl_or_b32 v1, v19, 16, v18
	v_lshl_or_b32 v2, v21, 16, v20
	v_lshl_or_b32 v3, v23, 16, v22
	global_store_dwordx4 v66, v[0:3], s[26:27]
	s_nop 1
	s_waitcnt vmcnt(48)
	v_lshl_or_b32 v0, v25, 16, v24
	v_lshl_or_b32 v1, v27, 16, v26
	v_lshl_or_b32 v2, v29, 16, v28
	v_lshl_or_b32 v3, v31, 16, v30
	global_store_dwordx4 v66, v[0:3], s[26:27] offset:2048
	s_nop 1
	s_waitcnt vmcnt(40)
	v_lshl_or_b32 v0, v33, 16, v32
	v_lshl_or_b32 v1, v35, 16, v34
	v_lshl_or_b32 v2, v37, 16, v36
	v_lshl_or_b32 v3, v39, 16, v38
	v_add_u32_e32 v15, 0x1000, v66
	global_store_dwordx4 v15, v[0:3], s[26:27]
	s_nop 1
	s_waitcnt vmcnt(32)
	v_lshl_or_b32 v0, v41, 16, v40
	v_lshl_or_b32 v1, v43, 16, v42
	v_lshl_or_b32 v2, v45, 16, v44
	v_lshl_or_b32 v3, v47, 16, v46
	v_add_u32_e32 v15, 0x1000, v66
	global_store_dwordx4 v15, v[0:3], s[26:27] offset:2048
	s_nop 1
	s_waitcnt vmcnt(24)
	v_lshl_or_b32 v0, v49, 16, v48
	v_lshl_or_b32 v1, v51, 16, v50
	v_lshl_or_b32 v2, v53, 16, v52
	v_lshl_or_b32 v3, v55, 16, v54
	v_add_u32_e32 v15, 0x2000, v66
	global_store_dwordx4 v15, v[0:3], s[26:27]
	s_nop 1
	s_waitcnt vmcnt(16)
	v_lshl_or_b32 v0, v57, 16, v56
	v_lshl_or_b32 v1, v59, 16, v58
	v_lshl_or_b32 v2, v61, 16, v60
	v_lshl_or_b32 v3, v63, 16, v62
	v_add_u32_e32 v15, 0x2000, v66
	global_store_dwordx4 v15, v[0:3], s[26:27] offset:2048
	s_nop 1
	s_waitcnt vmcnt(8)
	v_lshl_or_b32 v0, v179, 16, v178
	v_lshl_or_b32 v1, v181, 16, v180
	v_lshl_or_b32 v2, v183, 16, v182
	v_lshl_or_b32 v3, v185, 16, v184
	v_add_u32_e32 v15, 0x3000, v66
	global_store_dwordx4 v15, v[0:3], s[26:27]
	s_nop 1
	s_waitcnt vmcnt(0)
	v_lshl_or_b32 v0, v187, 16, v186
	v_lshl_or_b32 v1, v189, 16, v188
	v_lshl_or_b32 v2, v191, 16, v190
	v_lshl_or_b32 v3, v193, 16, v192
	v_add_u32_e32 v15, 0x3000, v66
	global_store_dwordx4 v15, v[0:3], s[26:27] offset:2048
	s_nop 1
	s_and_b64 vcc, exec, s[28:29]
	s_mov_b64 s[28:29], 0
	s_mov_b32 s0, 64
	s_cbranch_vccnz .LBB0_1516
	s_add_i32 s24, s24, s70
	s_cmpk_gt_i32 s24, 0x5ff
	s_cbranch_scc0 .LBB0_1513
